# attention: split the compiler-packed v_pk_fma_f32 beside the MFMAs into two v_fmamk_f32 (asm guide 7.5), fusing two feeding v_mov pairs; bit-identical
# speedup vs baseline: 1.0064x; 1.0035x over previous
; #define ALAS __attribute__((address_space(3)))
; __device__ __forceinline__ void partialSM(f32x16& p0, f32x16& p1, float& m_reg, float& mn, float& alpha) {
;   constexpr float C = SCALE * LOG2E;
;   float pmax = p0[0];
; #pragma unroll
;   for (int r = 1; r < 16; ++r) pmax = fmaxf(pmax, p0[r]);
; #pragma unroll
;   for (int r = 0; r < 16; ++r) pmax = fmaxf(pmax, p1[r]);
;   { auto rr = __builtin_amdgcn_permlane32_swap(__float_as_uint(pmax), __float_as_uint(pmax), false, false);
;     pmax = fmaxf(__uint_as_float(rr[0]), __uint_as_float(rr[1])); }
;   if (__builtin_expect(__all(pmax - m_reg <= THR / SCALE), 1)) { mn = m_reg; alpha = 1.f; }
;   else { mn = fmaxf(m_reg, pmax); alpha = __builtin_amdgcn_exp2f((m_reg - mn) * C); m_reg = mn; }
;   float mnC = -mn * C;
; #pragma unroll
;   for (int r = 0; r < 16; ++r) p0[r] = fmaf(p0[r], C, mnC);
; #pragma unroll
;   for (int r = 0; r < 16; ++r) p1[r] = fmaf(p1[r], C, mnC);
; #pragma unroll
;   for (int r = 0; r < 16; ++r) p0[r] = __builtin_amdgcn_exp2f(p0[r]);
; __device__ __forceinline__ void qkt(f32x16& p0, f32x16& p1, lptr Ks, const bf16x8* qr, int r32, int hi) {
; #pragma unroll
;   for (int d0 = 0; d0 < 8; ++d0) { int cb = (d0 * 16 + hi * 8) * 2;
;     bf16x8 b0 = *(const ALAS bf16x8*)(Ks + KSWZ(r32, cb));
;     bf16x8 b1 = *(const ALAS bf16x8*)(Ks + KSWZ(32 + r32, cb));
;     p0 = __builtin_amdgcn_mfma_f32_32x32x16_bf16(b0, qr[d0], p0, 0, 0, 0);
;     p1 = __builtin_amdgcn_mfma_f32_32x32x16_bf16(b1, qr[d0], p1, 0, 0, 0); }
.LBB0_458:
	v_lshlrev_b32_e32 v42, 4, v200
	v_lshlrev_b32_e32 v41, 3, v200
	v_and_b32_e32 v42, 0xc0, v42
	v_lshlrev_b32_e32 v43, 1, v200
	v_and_b32_e32 v223, 7, v40
	v_lshrrev_b32_e32 v40, 1, v40
	v_and_or_b32 v42, v41, 24, v42
	v_and_b32_e32 v43, 32, v43
	v_and_b32_e32 v41, 0x100, v41
	v_and_or_b32 v40, v40, 8, v223
	v_or3_b32 v225, v42, v43, v41
	v_lshlrev_b32_e32 v224, 4, v222
	v_lshlrev_b32_e32 v41, 8, v221
	v_lshlrev_b32_e32 v56, 4, v40
	v_add_u32_e32 v57, 0, v41
	v_xor_b32_e32 v45, v56, v224
	v_add_u32_e32 v238, v57, v45
	ds_read_b128 v[46:49], v238 offset:32768
	ds_read_b128 v[50:53], v238 offset:40960
	s_waitcnt lgkmcnt(1)
	v_mfma_f32_32x32x16_bf16 v[16:31], v[46:49], v[156:159], v[16:31]
	v_bitop3_b32 v40, v224, v56, 32 bitop3:0x36
	v_add_u32_e32 v237, v57, v40
	v_bitop3_b32 v42, v224, v56, 64 bitop3:0x36
	v_add_u32_e32 v236, v57, v42
	s_and_b32 s4, s7, 0x3fffffc0
	s_lshl_b32 s4, s4, 2
	s_add_i32 s31, s4, 0
	s_waitcnt lgkmcnt(0)
	v_mfma_f32_32x32x16_bf16 v[0:15], v[50:53], v[156:159], v[0:15]
	ds_read_b128 v[46:49], v237 offset:32768
	ds_read_b128 v[50:53], v237 offset:40960
	s_bfe_u32 s4, s1, 0x60019
	s_add_i32 s1, s1, s4
	s_sext_i32_i16 s1, s1
	s_ashr_i32 s18, s1, 6
	s_movk_i32 s1, 0x60
	v_bitop3_b32 v43, v224, v56, s1 bitop3:0x36
	s_waitcnt lgkmcnt(1)
	v_mfma_f32_32x32x16_bf16 v[16:31], v[46:49], v[152:155], v[16:31]
	v_add_u32_e32 v235, v57, v43
	s_movk_i32 s1, 0x80
	v_bitop3_b32 v44, v224, v56, s1 bitop3:0x36
	v_add_u32_e32 v234, v57, v44
	s_movk_i32 s1, 0xa0
	s_add_i32 s31, s31, 0x10000
	v_add_u32_e32 v226, 0, v225
	s_waitcnt lgkmcnt(0)
	v_mfma_f32_32x32x16_bf16 v[0:15], v[50:53], v[152:155], v[0:15]
	ds_read_b128 v[46:49], v236 offset:32768
	ds_read_b128 v[50:53], v236 offset:40960
	v_cmp_gt_u32_e64 s[36:37], 32, v200
	s_waitcnt lgkmcnt(1)
	v_mfma_f32_32x32x16_bf16 v[16:31], v[46:49], v[148:151], v[16:31]
	s_waitcnt lgkmcnt(0)
	v_mfma_f32_32x32x16_bf16 v[0:15], v[50:53], v[148:151], v[0:15]
	ds_read_b128 v[46:49], v235 offset:32768
	ds_read_b128 v[50:53], v235 offset:40960
	s_waitcnt lgkmcnt(1)
	v_mfma_f32_32x32x16_bf16 v[16:31], v[46:49], v[144:147], v[16:31]
	s_waitcnt lgkmcnt(0)
	v_mfma_f32_32x32x16_bf16 v[0:15], v[50:53], v[144:147], v[0:15]
	ds_read_b128 v[46:49], v234 offset:32768
	ds_read_b128 v[50:53], v234 offset:40960
	s_waitcnt lgkmcnt(1)
	v_mfma_f32_32x32x16_bf16 v[16:31], v[46:49], v[140:143], v[16:31]
	v_bitop3_b32 v46, v224, v56, s1 bitop3:0x36
	v_add_u32_e32 v233, v57, v46
	s_movk_i32 s1, 0xc0
	v_bitop3_b32 v47, v224, v56, s1 bitop3:0x36
	v_add_u32_e32 v232, v57, v47
	s_movk_i32 s1, 0xe0
	s_waitcnt lgkmcnt(0)
	v_mfma_f32_32x32x16_bf16 v[0:15], v[50:53], v[140:143], v[0:15]
	ds_read_b128 v[48:51], v233 offset:32768
	ds_read_b128 v[52:55], v233 offset:40960
	s_waitcnt lgkmcnt(1)
	v_mfma_f32_32x32x16_bf16 v[16:31], v[48:51], v[136:139], v[16:31]
	s_waitcnt lgkmcnt(0)
	v_mfma_f32_32x32x16_bf16 v[0:15], v[52:55], v[136:139], v[0:15]
	ds_read_b128 v[48:51], v232 offset:32768
	ds_read_b128 v[52:55], v232 offset:40960
	s_waitcnt lgkmcnt(1)
	v_mfma_f32_32x32x16_bf16 v[16:31], v[48:51], v[132:135], v[16:31]
	v_bitop3_b32 v48, v224, v56, s1 bitop3:0x36
	v_add_u32_e32 v230, v57, v48
	s_mov_b32 s1, 0x42b504f3
	s_waitcnt lgkmcnt(0)
	v_mfma_f32_32x32x16_bf16 v[0:15], v[52:55], v[132:135], v[0:15]
	ds_read_b128 v[50:53], v230 offset:32768
	ds_read_b128 v[54:57], v230 offset:40960
	s_waitcnt vmcnt(4)
	s_waitcnt vmcnt(1)
	ds_write_b128 v229, v[32:35] offset:49152
	s_waitcnt vmcnt(0)
	ds_write_b128 v231, v[36:39] offset:49152
	s_waitcnt lgkmcnt(0)
	s_barrier
	v_mfma_f32_32x32x16_bf16 v[16:31], v[50:53], v[128:131], v[16:31]
	v_mov_b32_e32 v51, 0xd01502f9
	v_mfma_f32_32x32x16_bf16 v[0:15], v[54:57], v[128:131], v[0:15]
	s_nop 9
	v_max_f32_e32 v49, v17, v17
	v_max_f32_e32 v50, v16, v16
	v_max_f32_e32 v49, v50, v49
	v_max3_f32 v49, v49, v18, v19
	v_max3_f32 v49, v49, v20, v21
	v_max3_f32 v49, v49, v22, v23
	v_max3_f32 v49, v49, v24, v25
	v_max3_f32 v49, v49, v26, v27
	v_max3_f32 v49, v49, v28, v29
	v_max3_f32 v49, v49, v30, v31
	v_max3_f32 v49, v49, v0, v1
	v_max3_f32 v49, v49, v2, v3
	v_max3_f32 v49, v49, v4, v5
	v_max3_f32 v49, v49, v6, v7
	v_max3_f32 v49, v49, v8, v9
	v_max3_f32 v49, v49, v10, v11
	v_max3_f32 v49, v49, v12, v13
	v_max3_f32 v49, v49, v14, v15
	v_mov_b32_e32 v50, v49
	s_nop 1
	v_permlane32_swap_b32_e32 v49, v50
	v_max_f32_e32 v50, v50, v50
	v_max_f32_e32 v49, v49, v49
	v_max_f32_e32 v49, v49, v50
	v_add_f32_e32 v50, 0x501502f9, v49
	v_max_f32_e32 v49, 0xd01502f9, v49
	v_cmp_ge_f32_e32 vcc, s1, v50
	v_sub_f32_e32 v50, 0xd01502f9, v49
	v_mul_f32_e32 v50, 0x3e0293ee, v50
	v_exp_f32_e32 v50, v50
	s_cmp_eq_u64 vcc, exec
	s_cselect_b64 vcc, -1, 0
	v_cndmask_b32_e32 v192, v49, v51, vcc
	v_cndmask_b32_e64 v193, v50, 1.0, vcc
	v_mul_f32_e32 v50, 0xbe0293ee, v192
	v_mov_b32_e32 v49, v50
	v_fmamk_f32 v16, v16, 0x3e0293ee, v50
	v_fmamk_f32 v17, v17, 0x3e0293ee, v50
	v_fmamk_f32 v18, v18, 0x3e0293ee, v50
	v_fmamk_f32 v19, v19, 0x3e0293ee, v50
	v_fmamk_f32 v20, v20, 0x3e0293ee, v50
	v_fmamk_f32 v21, v21, 0x3e0293ee, v50
	v_fmamk_f32 v22, v22, 0x3e0293ee, v50
	v_fmamk_f32 v23, v23, 0x3e0293ee, v50
	v_fmamk_f32 v24, v24, 0x3e0293ee, v50
	v_fmamk_f32 v25, v25, 0x3e0293ee, v50
	v_fmamk_f32 v26, v26, 0x3e0293ee, v50
	v_fmamk_f32 v27, v27, 0x3e0293ee, v50
	v_fmamk_f32 v28, v28, 0x3e0293ee, v50
	v_fmamk_f32 v29, v29, 0x3e0293ee, v50
	v_fmamk_f32 v30, v30, 0x3e0293ee, v50
	v_fmac_f32_e32 v49, 0x3e0293ee, v31
	v_exp_f32_e32 v80, v16
	v_exp_f32_e32 v81, v17
	v_exp_f32_e32 v82, v18
	v_exp_f32_e32 v83, v19
	v_exp_f32_e32 v84, v20
	v_exp_f32_e32 v85, v21
	v_exp_f32_e32 v86, v22
	v_exp_f32_e32 v87, v23
	v_exp_f32_e32 v88, v24
	v_exp_f32_e32 v89, v25
	v_exp_f32_e32 v90, v26
	v_exp_f32_e32 v91, v27
	v_exp_f32_e32 v92, v28
	v_exp_f32_e32 v93, v29
	v_exp_f32_e32 v94, v30
	v_exp_f32_e32 v95, v49
	v_fmamk_f32 v78, v14, 0x3e0293ee, v50
	v_fmamk_f32 v79, v15, 0x3e0293ee, v50
	v_fmamk_f32 v76, v12, 0x3e0293ee, v50
	v_fmamk_f32 v77, v13, 0x3e0293ee, v50
	v_fmamk_f32 v74, v10, 0x3e0293ee, v50
	v_fmamk_f32 v75, v11, 0x3e0293ee, v50
	v_fmamk_f32 v72, v8, 0x3e0293ee, v50
	v_fmamk_f32 v73, v9, 0x3e0293ee, v50
	v_fmamk_f32 v70, v6, 0x3e0293ee, v50
	v_fmamk_f32 v71, v7, 0x3e0293ee, v50
	v_fmamk_f32 v68, v4, 0x3e0293ee, v50
	v_fmamk_f32 v69, v5, 0x3e0293ee, v50
	v_fmamk_f32 v66, v2, 0x3e0293ee, v50
	v_fmamk_f32 v67, v3, 0x3e0293ee, v50
	v_fmamk_f32 v64, v0, 0x3e0293ee, v50
	v_fmamk_f32 v65, v1, 0x3e0293ee, v50
	v_mov_b32_e32 v15, 0
	s_andn2_b64 vcc, exec, s[2:3]
	s_cbranch_vccnz .LBB0_496
; #define ALAS __attribute__((address_space(3)))
; __device__ __forceinline__ void bias_init(f32x16& p0, f32x16& p1, int mode, int k0, int qw, int r32, int hi, const ALAS float* tab) {
;   if (mode == MODE_B) { p0 = f32x16{}; p1 = f32x16{}; return; }
;   if (mode == MODE_A) {
;     const int kr = k0 >> 6, rq = qw >> 6, rs = min(max(rq - 4, 0), 24);
;     if (kr < rs || kr >= rs + 8) {
; #pragma unroll
;       for (int r = 0; r < 16; ++r) { p0[r] = MASKV; p1[r] = MASKV; } }
;     else { const int cq = (qw & 63) + r32, cs = min(max(cq - 8, 0), 48), d = 4 * hi - cs; const ALAS float* rt = tab + ((kr - rq + 7) * 128 + 48 + 15 + 4 * hi - cq); asm volatile("" : "+v"(rt));
; #pragma unroll
;       for (int r = 0; r < 16; ++r) { const int c0 = (r & 3) + 8 * (r >> 2), c1 = c0 + 32; const bool ok0 = (unsigned)(c0 + d) < 16u, ok1 = (unsigned)(c1 + d) < 16u;
;         const float t0 = rt[c0], t1 = rt[c1]; p0[r] = ok0 ? t0 : MASKV; p1[r] = ok1 ? t1 : MASKV; if ((r & 3) == 3) asm volatile("" ::: "memory"); } }
	v_and_or_b32 v239, s40, 32, v221
	v_sub_u32_e64 v1, v239, 8 clamp
	v_min_u32_e32 v1, 48, v1
	v_lshlrev_b32_e32 v2, 2, v222
	v_sub_u32_e32 v1, v2, v1
	v_and_b32_e32 v2, -16, v1
	v_add_u32_e32 v3, 1, v1
	v_writelane_b32 v255, s40, 19
	s_mov_b32 s10, s41
	v_cmp_eq_u32_e64 s[40:41], s89, v2
	s_mov_b32 s11, s42
	v_cmp_gt_u32_e64 s[42:43], 16, v3
	v_add_u32_e32 v3, 33, v1
	v_cmp_eq_u32_e64 s[72:73], s90, v2
	v_add_u32_e32 v2, 17, v1
	v_cmp_gt_u32_e64 s[44:45], 16, v3
	v_add_u32_e32 v3, 2, v1
	v_cmp_gt_u32_e64 s[74:75], 16, v2
	v_add_u32_e32 v2, 49, v1
	v_cmp_gt_u32_e64 s[46:47], 16, v3
	v_add_u32_e32 v3, 34, v1
	v_cmp_gt_u32_e64 s[76:77], 16, v2
	v_add_u32_e32 v2, 18, v1
	v_cmp_gt_u32_e64 s[48:49], 16, v3
	v_add_u32_e32 v3, 3, v1
	v_cmp_gt_u32_e64 s[78:79], 16, v2
	v_add_u32_e32 v2, 50, v1
	v_cmp_gt_u32_e64 s[50:51], 16, v3
	v_add_u32_e32 v3, 35, v1
	v_cmp_gt_u32_e64 s[80:81], 16, v2
	v_add_u32_e32 v2, 19, v1
	v_cmp_gt_u32_e64 s[52:53], 16, v3
	v_add_u32_e32 v3, 8, v1
	v_cmp_gt_u32_e64 s[82:83], 16, v2
	v_add_u32_e32 v2, 51, v1
	v_cmp_gt_u32_e64 s[54:55], 16, v3
	v_add_u32_e32 v3, 40, v1
	v_cmp_gt_u32_e64 s[84:85], 16, v2
	v_add_u32_e32 v2, 24, v1
	s_ashr_i32 s22, s30, 6
	v_cmp_gt_u32_e64 s[56:57], 16, v3
	v_add_u32_e32 v3, 9, v1
	v_cmp_gt_u32_e64 s[86:87], 16, v2
	v_add_u32_e32 v2, 56, v1
	s_max_i32 s1, s22, 4
	v_cmp_gt_u32_e64 s[58:59], 16, v3
	v_add_u32_e32 v3, 41, v1
	v_cmp_gt_u32_e64 s[88:89], 16, v2
	v_add_u32_e32 v2, 25, v1
	s_add_i32 s1, s1, -4
	v_cmp_gt_u32_e64 s[60:61], 16, v3
	v_add_u32_e32 v3, 10, v1
	v_cmp_lt_u32_e64 s[70:71], s91, v1
	v_cmp_gt_u32_e64 s[90:91], 16, v2
	v_add_u32_e32 v2, 57, v1
	s_min_u32 s7, s1, 24
	v_cmp_gt_u32_e64 s[62:63], 16, v3
	v_add_u32_e32 v3, 42, v1
	v_cmp_gt_u32_e64 s[92:93], 16, v2
	v_add_u32_e32 v2, 26, v1
	v_lshlrev_b32_e32 v8, 2, v221
	v_readlane_b32 s1, v254, 21
	v_lshl_add_u32 v9, s11, 2, v224
	v_cmp_gt_u32_e64 s[64:65], 16, v3
	v_add_u32_e32 v3, 11, v1
	v_cmp_gt_u32_e64 s[94:95], 16, v2
	v_add_u32_e32 v2, 58, v1
	v_add_u32_e32 v240, s31, v8
	v_lshl_add_u32 v241, v222, 4, s1
	v_sub_u32_e32 v8, v9, v8
	s_lshl_b32 s1, s10, 7
	s_add_i32 s19, s18, -3
	s_add_i32 s27, s7, 8
	v_cmp_gt_u32_e64 s[38:39], 16, v1
	v_cmp_gt_u32_e64 s[66:67], 16, v3
	v_add_u32_e32 v3, 43, v1
	v_cmp_gt_u32_e64 s[96:97], 16, v2
	v_add_u32_e32 v2, 27, v1
	v_add_u32_e32 v1, 59, v1
	v_writelane_b32 v255, s30, 20
	s_sub_i32 s30, 0, s30
	v_subrev_u32_e32 v8, s1, v8
	s_lshl_b32 s1, s20, 10
	v_or_b32_e32 v0, v45, v41
	v_cmp_gt_u32_e64 s[68:69], 16, v3
	v_cmp_gt_u32_e64 s[2:3], 16, v2
	v_cmp_gt_u32_e64 s[4:5], 16, v1
	v_or_b32_e32 v1, v40, v41
	v_or_b32_e32 v2, v42, v41
	v_or_b32_e32 v3, v43, v41
	v_or_b32_e32 v4, v44, v41
	v_or_b32_e32 v5, v46, v41
	v_or_b32_e32 v6, v47, v41
	v_or_b32_e32 v7, v48, v41
	v_writelane_b32 v255, s10, 21
	v_subrev_u32_e32 v8, s1, v8
	v_readlane_b32 s1, v254, 22
	s_add_u32 s14, s8, s14
	v_mov_b32_e32 v194, 0
	s_mov_b32 s12, 2
	v_add_u32_e32 v242, s1, v8
	s_addc_u32 s15, s9, s15
	v_add_u32_e32 v243, 0, v0
	v_add_u32_e32 v244, 0, v1
	v_add_u32_e32 v245, 0, v2
	v_add_u32_e32 v246, 0, v3
	v_add_u32_e32 v247, 0, v4
	v_add_u32_e32 v248, 0, v5
	v_add_u32_e32 v249, 0, v6
	v_add_u32_e32 v250, 0, v7
	v_writelane_b32 v255, s11, 22
	s_mov_b32 s20, s11
	v_mov_b32_e32 v48, 0
	v_mov_b32_e32 v49, v194
	v_mov_b32_e32 v50, v194
	v_mov_b32_e32 v51, v194
	v_mov_b32_e32 v52, v194
	v_mov_b32_e32 v53, v194
	v_mov_b32_e32 v54, v194
	v_mov_b32_e32 v55, v194
	v_mov_b32_e32 v56, v194
	v_mov_b32_e32 v57, v194
	v_mov_b32_e32 v58, v194
	v_mov_b32_e32 v59, v194
	v_mov_b32_e32 v60, v194
	v_mov_b32_e32 v61, v194
	v_mov_b32_e32 v62, v194
	v_mov_b32_e32 v63, v194
	v_mov_b32_e32 v32, 0
	v_mov_b32_e32 v33, v194
	v_mov_b32_e32 v34, v194
	v_mov_b32_e32 v35, v194
	v_mov_b32_e32 v36, v194
	v_mov_b32_e32 v37, v194
	v_mov_b32_e32 v38, v194
	v_mov_b32_e32 v39, v194
	v_mov_b32_e32 v40, v194
	v_mov_b32_e32 v41, v194
	v_mov_b32_e32 v42, v194
	v_mov_b32_e32 v43, v194
	v_mov_b32_e32 v44, v194
	v_mov_b32_e32 v45, v194
	v_mov_b32_e32 v46, v194
	v_mov_b32_e32 v47, v194
	v_mov_b32_e32 v16, 0
	v_mov_b32_e32 v17, v194
	v_mov_b32_e32 v18, v194
	v_mov_b32_e32 v19, v194
	v_mov_b32_e32 v20, v194
	v_mov_b32_e32 v21, v194
	v_mov_b32_e32 v22, v194
	v_mov_b32_e32 v23, v194
	v_mov_b32_e32 v24, v194
	v_mov_b32_e32 v25, v194
	v_mov_b32_e32 v26, v194
	v_mov_b32_e32 v27, v194
	v_mov_b32_e32 v28, v194
	v_mov_b32_e32 v29, v194
	v_mov_b32_e32 v30, v194
	v_mov_b32_e32 v31, v194
	v_mov_b32_e32 v0, 0
	v_mov_b32_e32 v1, v194
	v_mov_b32_e32 v2, v194
	v_mov_b32_e32 v3, v194
	v_mov_b32_e32 v4, v194
	v_mov_b32_e32 v5, v194
	v_mov_b32_e32 v6, v194
	v_mov_b32_e32 v7, v194
	v_mov_b32_e32 v8, v194
	v_mov_b32_e32 v9, v194
	v_mov_b32_e32 v10, v194
	v_mov_b32_e32 v11, v194
	v_mov_b32_e32 v12, v194
	v_mov_b32_e32 v13, v194
	v_mov_b32_e32 v14, v194
	v_mov_b32_e32 v15, v194

.LBB0_472:
	s_waitcnt lgkmcnt(0)
	s_nop 0
	v_mfma_f32_32x32x16_bf16 v[112:127], v[184:187], v[156:159], v[112:127]
	ds_read_b128 v[176:179], v244 offset:49152
	ds_read_b128 v[180:183], v237 offset:57344
	v_add_f32_e32 v184, v80, v81
	v_add_f32_e32 v184, v82, v184
	v_exp_f32_e32 v64, v64
	v_exp_f32_e32 v65, v65
	v_exp_f32_e32 v66, v66
	v_add_f32_e32 v195, v83, v184
	v_mfma_f32_32x32x16_bf16 v[96:111], v[188:191], v[156:159], v[96:111]
	v_cvt_pk_bf16_f32 v80, v80, v81
	v_cvt_pk_bf16_f32 v81, v82, v83
	s_nop 0
	s_waitcnt lgkmcnt(1)
	v_mfma_f32_32x32x16_bf16 v[112:127], v[176:179], v[152:155], v[112:127]
	ds_read_b128 v[184:187], v245 offset:49152
	ds_read_b128 v[188:191], v236 offset:57344
	v_add_f32_e32 v82, v84, v195
	v_add_f32_e32 v82, v85, v82
	v_add_f32_e32 v82, v86, v82
	v_cvt_pk_bf16_f32 v83, v86, v87
	v_exp_f32_e32 v67, v67
	v_exp_f32_e32 v68, v68
	s_waitcnt lgkmcnt(2)
	v_mfma_f32_32x32x16_bf16 v[96:111], v[180:183], v[152:155], v[96:111]
	v_add_f32_e32 v180, v87, v82
	v_cvt_pk_bf16_f32 v82, v84, v85
	v_exp_f32_e32 v69, v69
	v_permlane32_swap_b32_e32 v80, v82
	v_permlane32_swap_b32_e32 v81, v83
	s_waitcnt lgkmcnt(1)
	v_mfma_f32_32x32x16_bf16 v[112:127], v[184:187], v[148:151], v[112:127]
	ds_read_b128 v[84:87], v246 offset:49152
	ds_read_b128 v[176:179], v235 offset:57344
	v_add_f32_e32 v180, v88, v180
	v_add_f32_e32 v180, v89, v180
	v_add_f32_e32 v180, v90, v180
	v_exp_f32_e32 v70, v70
	v_exp_f32_e32 v71, v71
	v_exp_f32_e32 v72, v72
	s_waitcnt lgkmcnt(2)
	v_mfma_f32_32x32x16_bf16 v[96:111], v[188:191], v[148:151], v[96:111]
	v_add_f32_e32 v188, v91, v180
	v_cvt_pk_bf16_f32 v88, v88, v89
	v_cvt_pk_bf16_f32 v89, v90, v91
	s_nop 0
	s_waitcnt lgkmcnt(1)
	v_mfma_f32_32x32x16_bf16 v[112:127], v[84:87], v[144:147], v[112:127]
	ds_read_b128 v[180:183], v247 offset:49152
	ds_read_b128 v[184:187], v234 offset:57344
	v_add_f32_e32 v84, v92, v188
	v_add_f32_e32 v84, v93, v84
	v_add_f32_e32 v84, v94, v84
	v_cvt_pk_bf16_f32 v90, v92, v93
	v_cvt_pk_bf16_f32 v91, v94, v95
	v_exp_f32_e32 v73, v73
	s_waitcnt lgkmcnt(2)
	v_mfma_f32_32x32x16_bf16 v[96:111], v[176:179], v[144:147], v[96:111]
	v_exp_f32_e32 v74, v74
	v_exp_f32_e32 v75, v75
	v_add_f32_e32 v84, v95, v84
	v_permlane32_swap_b32_e32 v88, v90
	v_permlane32_swap_b32_e32 v89, v91
	s_waitcnt lgkmcnt(1)
	v_mfma_f32_32x32x16_bf16 v[112:127], v[180:183], v[140:143], v[112:127]
	ds_read_b128 v[92:95], v248 offset:49152
	ds_read_b128 v[176:179], v233 offset:57344
	v_add_f32_e32 v84, v84, v64
	v_add_f32_e32 v84, v65, v84
	v_add_f32_e32 v84, v66, v84
	v_exp_f32_e32 v76, v76
	v_exp_f32_e32 v77, v77
	v_add_f32_e32 v86, v67, v84
	s_waitcnt lgkmcnt(2)
	v_mfma_f32_32x32x16_bf16 v[96:111], v[184:187], v[140:143], v[96:111]
	v_cvt_pk_bf16_f32 v84, v64, v65
	v_cvt_pk_bf16_f32 v85, v66, v67
	s_nop 0
	s_waitcnt lgkmcnt(1)
	v_mfma_f32_32x32x16_bf16 v[112:127], v[92:95], v[136:139], v[112:127]
	ds_read_b128 v[180:183], v249 offset:49152
	ds_read_b128 v[184:187], v232 offset:57344
	v_add_f32_e32 v86, v86, v68
	v_add_f32_e32 v86, v69, v86
	v_add_f32_e32 v86, v70, v86
	v_cvt_pk_bf16_f32 v87, v70, v71
	v_exp_f32_e32 v78, v78
	v_exp_f32_e32 v79, v79
	s_waitcnt lgkmcnt(2)
	v_mfma_f32_32x32x16_bf16 v[96:111], v[176:179], v[136:139], v[96:111]
	v_add_f32_e32 v176, v71, v86
	v_cvt_pk_bf16_f32 v86, v68, v69
	v_permlane32_swap_b32_e32 v85, v87
	v_permlane32_swap_b32_e32 v84, v86
	s_waitcnt lgkmcnt(1)
	v_mfma_f32_32x32x16_bf16 v[112:127], v[180:183], v[132:135], v[112:127]
	ds_read_b128 v[66:69], v250 offset:49152
	ds_read_b128 v[92:95], v230 offset:57344
	v_add_f32_e32 v64, v176, v72
	v_add_f32_e32 v64, v73, v64
	v_add_f32_e32 v64, v74, v64
	v_add_f32_e32 v176, v75, v64
	v_cvt_pk_bf16_f32 v64, v72, v73
	v_cvt_pk_bf16_f32 v65, v74, v75
	s_waitcnt lgkmcnt(2)
	v_mfma_f32_32x32x16_bf16 v[96:111], v[184:187], v[132:135], v[96:111]
	s_waitcnt lgkmcnt(1)
	v_mfma_f32_32x32x16_bf16 v[112:127], v[66:69], v[128:131], v[112:127]
	v_add_f32_e32 v66, v76, v176
	ds_read_b64_tr_b16 v[68:69], v226
	ds_read_b64_tr_b16 v[70:71], v226 offset:2048
	ds_read_b64_tr_b16 v[72:73], v226 offset:512
	ds_read_b64_tr_b16 v[74:75], v226 offset:2560
	v_add_f32_e32 v66, v77, v66
	v_add_f32_e32 v66, v78, v66
	v_cvt_pk_bf16_f32 v67, v78, v79
	s_nop 0
	v_permlane32_swap_b32_e32 v65, v67
	s_waitcnt lgkmcnt(4)
	v_mfma_f32_32x32x16_bf16 v[96:111], v[92:95], v[128:131], v[96:111]
	v_add_f32_e32 v92, v79, v66
	v_cvt_pk_bf16_f32 v66, v76, v77
	v_mov_b32_e32 v76, v92
	s_nop 1
	v_permlane32_swap_b32_e32 v92, v76
	v_add_f32_e32 v252, v92, v76
	v_permlane32_swap_b32_e32 v64, v66
	v_fmac_f32_e32 v252, v193, v194
	v_lshl_add_u64 v[210:211], s[14:15], 0, v[206:207]
	s_mov_b32 s1, 0x360000
	v_add_co_u32_e32 v76, vcc, s1, v210
	s_mov_b32 s10, 0x3f0000
	s_nop 0
	v_addc_co_u32_e32 v77, vcc, 0, v211, vcc
	v_add_co_u32_e32 v78, vcc, s10, v210
	v_lshl_add_u64 v[208:209], s[8:9], 0, v[206:207]
	s_nop 0
	v_addc_co_u32_e32 v79, vcc, 0, v211, vcc
	global_load_dwordx4 v[176:179], v[76:77], off
	global_load_dwordx4 v[180:183], v[78:79], off
	v_add_co_u32_e32 v76, vcc, s1, v208
	s_waitcnt lgkmcnt(2)
	v_mfma_f32_32x32x16_bf16 v[48:63], v[80:83], v[68:71], v[48:63]
	v_addc_co_u32_e32 v77, vcc, 0, v209, vcc
	v_add_co_u32_e32 v78, vcc, s10, v208
	s_nop 1
	v_addc_co_u32_e32 v79, vcc, 0, v209, vcc
	global_load_dwordx4 v[184:187], v[76:77], off
	global_load_dwordx4 v[188:191], v[78:79], off
	s_waitcnt lgkmcnt(0)
	v_mfma_f32_32x32x16_bf16 v[32:47], v[80:83], v[72:75], v[32:47]
	ds_read_b64_tr_b16 v[68:69], v226 offset:4096
	ds_read_b64_tr_b16 v[70:71], v226 offset:6144
	ds_read_b64_tr_b16 v[78:79], v226 offset:6656
	ds_read_b64_tr_b16 v[76:77], v226 offset:4608
	v_max3_f32 v72, v112, v113, v96
	v_max3_f32 v73, v114, v115, v97
	v_max3_f32 v72, v72, v98, v99
	v_max3_f32 v72, v72, v116, v117
	v_max3_f32 v73, v73, v118, v119
	v_max3_f32 v193, v72, v100, v101
	v_max3_f32 v194, v73, v102, v103
	s_waitcnt lgkmcnt(2)
	v_mfma_f32_32x32x16_bf16 v[48:63], v[88:91], v[68:71], v[48:63]
	v_max_f32_e32 v68, v193, v193
	v_max_f32_e32 v69, v120, v120
	v_max_f32_e32 v68, v68, v69
	v_max3_f32 v69, v194, v122, v123
	v_max3_f32 v68, v68, v121, v104
	v_max3_f32 v69, v69, v106, v107
	v_max3_f32 v68, v68, v105, v124
	v_max3_f32 v69, v69, v126, v127
	v_max3_f32 v68, v68, v125, v108
	v_max3_f32 v69, v69, v110, v111
	v_max3_f32 v68, v68, v109, v69
	v_mov_b32_e32 v69, v68
	s_nop 1
	v_permlane32_swap_b32_e32 v68, v69
	v_max_f32_e32 v69, v69, v69
	v_max_f32_e32 v68, v68, v68
	v_max_f32_e32 v68, v68, v69
	v_sub_f32_e32 v69, v68, v192
	s_mov_b32 s1, 0x42b504f3
	v_cmp_ge_f32_e32 vcc, s1, v69
	v_max_f32_e32 v69, v192, v192
	s_waitcnt lgkmcnt(0)
	v_mfma_f32_32x32x16_bf16 v[32:47], v[88:91], v[76:79], v[32:47]
	v_max_f32_e32 v68, v69, v68
	ds_read_b64_tr_b16 v[72:73], v226 offset:8192
	ds_read_b64_tr_b16 v[74:75], v226 offset:10240
	ds_read_b64_tr_b16 v[92:93], v226 offset:8704
	ds_read_b64_tr_b16 v[94:95], v226 offset:10752
	v_sub_f32_e32 v69, v192, v68
	v_mul_f32_e32 v69, 0x3e0293ee, v69
	v_exp_f32_e32 v69, v69
	s_cmp_eq_u64 vcc, exec
	s_cselect_b64 vcc, -1, 0
	v_cndmask_b32_e32 v251, v68, v192, vcc
	v_cndmask_b32_e64 v220, v69, 1.0, vcc
	v_mul_f32_e32 v68, 0xbe0293ee, v251
	s_waitcnt lgkmcnt(2)
	v_mfma_f32_32x32x16_bf16 v[48:63], v[84:87], v[72:75], v[48:63]
	ds_read_b64_tr_b16 v[70:71], v226 offset:12288
	ds_read_b64_tr_b16 v[72:73], v226 offset:14336
	ds_read_b64_tr_b16 v[76:77], v226 offset:14848
	ds_read_b64_tr_b16 v[74:75], v226 offset:12800
	v_fmamk_f32 v69, v112, 0x3e0293ee, v68
	v_exp_f32_e32 v112, v69
	v_fmamk_f32 v69, v113, 0x3e0293ee, v68
	v_exp_f32_e32 v113, v69
	v_fmamk_f32 v69, v114, 0x3e0293ee, v68
	v_exp_f32_e32 v114, v69
	s_waitcnt lgkmcnt(4)
	v_mfma_f32_32x32x16_bf16 v[32:47], v[84:87], v[92:95], v[32:47]
	v_fma_f32 v96, v96, s28, v68
	v_fma_f32 v97, v97, s28, v68
	v_fmamk_f32 v98, v98, 0x3e0293ee, v68
	s_waitcnt lgkmcnt(2)
	v_mfma_f32_32x32x16_bf16 v[48:63], v[64:67], v[70:73], v[48:63]
	ds_read_b64_tr_b16 v[92:93], v226 offset:1024
	ds_read_b64_tr_b16 v[94:95], v226 offset:3072
	ds_read_b64_tr_b16 v[192:193], v226 offset:1536
	ds_read_b64_tr_b16 v[194:195], v226 offset:3584
	v_fmamk_f32 v69, v115, 0x3e0293ee, v68
	v_exp_f32_e32 v115, v69
	v_fmamk_f32 v69, v116, 0x3e0293ee, v68
	v_mov_b32_e32 v70, v99
	v_mov_b32_e32 v71, v100
	v_exp_f32_e32 v116, v69
	s_waitcnt lgkmcnt(4)
	v_mfma_f32_32x32x16_bf16 v[32:47], v[64:67], v[74:77], v[32:47]
	v_fma_f32 v70, v70, s28, v68
	v_fma_f32 v71, v71, s28, v68
	v_fmamk_f32 v69, v117, 0x3e0293ee, v68
	v_exp_f32_e32 v117, v69
	v_fmamk_f32 v101, v101, 0x3e0293ee, v68
	v_mov_b32_e32 v99, v70
	v_mov_b32_e32 v100, v71
	s_waitcnt lgkmcnt(2)
	v_mfma_f32_32x32x16_bf16 v[16:31], v[80:83], v[92:95], v[16:31]
	ds_read_b64_tr_b16 v[70:71], v226 offset:5120
	ds_read_b64_tr_b16 v[72:73], v226 offset:7168
	ds_read_b64_tr_b16 v[76:77], v226 offset:7680
	ds_read_b64_tr_b16 v[74:75], v226 offset:5632
	v_fmamk_f32 v69, v118, 0x3e0293ee, v68
	v_exp_f32_e32 v118, v69
	v_fmamk_f32 v69, v119, 0x3e0293ee, v68
	v_exp_f32_e32 v119, v69
	v_fmamk_f32 v69, v120, 0x3e0293ee, v68
	v_exp_f32_e32 v120, v69
	s_waitcnt lgkmcnt(4)
	v_mfma_f32_32x32x16_bf16 v[0:15], v[80:83], v[192:195], v[0:15]
	v_fma_f32 v102, v102, s28, v68
	v_fma_f32 v103, v103, s28, v68
	v_fmamk_f32 v104, v104, 0x3e0293ee, v68
	s_waitcnt lgkmcnt(2)
	v_mfma_f32_32x32x16_bf16 v[16:31], v[88:91], v[70:73], v[16:31]
	ds_read_b64_tr_b16 v[78:79], v226 offset:9216
	ds_read_b64_tr_b16 v[80:81], v226 offset:11264
	ds_read_b64_tr_b16 v[92:93], v226 offset:9728
	ds_read_b64_tr_b16 v[94:95], v226 offset:11776
	v_fmamk_f32 v69, v121, 0x3e0293ee, v68
	v_exp_f32_e32 v121, v69
	v_fmamk_f32 v69, v122, 0x3e0293ee, v68
	v_mov_b32_e32 v70, v105
	v_mov_b32_e32 v71, v106
	v_exp_f32_e32 v122, v69
	s_waitcnt lgkmcnt(4)
	v_mfma_f32_32x32x16_bf16 v[0:15], v[88:91], v[74:77], v[0:15]
	v_fma_f32 v70, v70, s28, v68
	v_fma_f32 v71, v71, s28, v68
	v_fmamk_f32 v69, v123, 0x3e0293ee, v68
	v_exp_f32_e32 v123, v69
	v_fmamk_f32 v107, v107, 0x3e0293ee, v68
	v_mov_b32_e32 v105, v70
	v_mov_b32_e32 v106, v71
	s_waitcnt lgkmcnt(2)
	v_mfma_f32_32x32x16_bf16 v[16:31], v[84:87], v[78:81], v[16:31]
	ds_read_b64_tr_b16 v[70:71], v226 offset:13312
	ds_read_b64_tr_b16 v[72:73], v226 offset:15360
	ds_read_b64_tr_b16 v[76:77], v226 offset:15872
	ds_read_b64_tr_b16 v[74:75], v226 offset:13824
	v_fmamk_f32 v69, v124, 0x3e0293ee, v68
	v_exp_f32_e32 v124, v69
	v_fmamk_f32 v69, v125, 0x3e0293ee, v68
	v_exp_f32_e32 v125, v69
	v_fmamk_f32 v108, v108, 0x3e0293ee, v68
	v_fmamk_f32 v109, v109, 0x3e0293ee, v68
	s_waitcnt lgkmcnt(4)
	v_mfma_f32_32x32x16_bf16 v[0:15], v[84:87], v[92:95], v[0:15]
	s_waitcnt lgkmcnt(2)
	v_mfma_f32_32x32x16_bf16 v[16:31], v[64:67], v[70:73], v[16:31]
	v_fmamk_f32 v69, v126, 0x3e0293ee, v68
	v_exp_f32_e32 v126, v69
	v_mov_b32_e32 v69, v68
	v_fmac_f32_e32 v69, 0x3e0293ee, v127
	v_exp_f32_e32 v127, v69
	v_fmamk_f32 v110, v110, 0x3e0293ee, v68
	v_fmamk_f32 v111, v111, 0x3e0293ee, v68
	s_waitcnt lgkmcnt(0)
	v_mfma_f32_32x32x16_bf16 v[0:15], v[64:67], v[74:77], v[0:15]
	s_waitcnt vmcnt(4)
	v_cmp_gt_f32_e32 vcc, 1.0, v220
	ds_write_b128 v229, v[168:171] offset:32768
	ds_write_b128 v231, v[172:175] offset:32768
	s_cbranch_vccz .LBB0_476
	s_and_saveexec_b64 s[16:17], s[36:37]
	ds_write_b32 v240, v220 offset:128
	s_or_b64 exec, exec, s[16:17]
	s_waitcnt lgkmcnt(0)
	v_add_u32_e32 v76, s31, v224
	ds_read_b128 v[64:67], v76 offset:224
	ds_read_b128 v[68:71], v76 offset:192
	ds_read_b128 v[72:75], v76 offset:160
	ds_read_b128 v[76:79], v76 offset:128
	s_waitcnt lgkmcnt(3)
	v_pk_mul_f32 v[60:61], v[60:61], v[64:65]
	s_waitcnt lgkmcnt(2)
	v_pk_mul_f32 v[56:57], v[56:57], v[68:69]
	s_waitcnt lgkmcnt(1)
	v_pk_mul_f32 v[52:53], v[52:53], v[72:73]
	v_pk_mul_f32 v[62:63], v[62:63], v[66:67]
	v_pk_mul_f32 v[58:59], v[58:59], v[70:71]
	v_pk_mul_f32 v[54:55], v[54:55], v[74:75]
	s_waitcnt lgkmcnt(0)
	v_pk_mul_f32 v[50:51], v[50:51], v[78:79]
	v_pk_mul_f32 v[48:49], v[48:49], v[76:77]
	v_pk_mul_f32 v[44:45], v[44:45], v[64:65]
	v_pk_mul_f32 v[40:41], v[40:41], v[68:69]
	v_pk_mul_f32 v[36:37], v[36:37], v[72:73]
	v_pk_mul_f32 v[46:47], v[46:47], v[66:67]
	v_pk_mul_f32 v[42:43], v[42:43], v[70:71]
	v_pk_mul_f32 v[38:39], v[38:39], v[74:75]
	v_pk_mul_f32 v[34:35], v[34:35], v[78:79]
	v_pk_mul_f32 v[32:33], v[32:33], v[76:77]
	v_pk_mul_f32 v[28:29], v[28:29], v[64:65]
	v_pk_mul_f32 v[24:25], v[24:25], v[68:69]
	v_pk_mul_f32 v[20:21], v[20:21], v[72:73]
	v_pk_mul_f32 v[30:31], v[30:31], v[66:67]
	v_pk_mul_f32 v[26:27], v[26:27], v[70:71]
	v_pk_mul_f32 v[22:23], v[22:23], v[74:75]
	v_pk_mul_f32 v[18:19], v[18:19], v[78:79]
	v_pk_mul_f32 v[16:17], v[16:17], v[76:77]
	v_pk_mul_f32 v[12:13], v[12:13], v[64:65]
	v_pk_mul_f32 v[8:9], v[8:9], v[68:69]
	v_pk_mul_f32 v[4:5], v[4:5], v[72:73]
	v_pk_mul_f32 v[14:15], v[14:15], v[66:67]
	v_pk_mul_f32 v[10:11], v[10:11], v[70:71]
	v_pk_mul_f32 v[6:7], v[6:7], v[74:75]
	v_pk_mul_f32 v[2:3], v[2:3], v[78:79]
	v_pk_mul_f32 v[0:1], v[0:1], v[76:77]

.LBB0_490:
	s_waitcnt lgkmcnt(2)
	v_mfma_f32_32x32x16_bf16 v[48:63], v[112:115], v[100:103], v[48:63]
	ds_read_b64_tr_b16 v[108:109], v226 offset:20480
	ds_read_b64_tr_b16 v[110:111], v226 offset:22528
	ds_read_b64_tr_b16 v[124:125], v226 offset:20992
	ds_read_b64_tr_b16 v[126:127], v226 offset:23040
	v_max3_f32 v100, v80, v81, v64
	v_max3_f32 v101, v82, v83, v65
	v_max3_f32 v100, v100, v66, v67
	v_max3_f32 v100, v100, v84, v85
	v_max3_f32 v101, v101, v86, v87
	v_max3_f32 v100, v100, v68, v69
	s_waitcnt lgkmcnt(4)
	v_mfma_f32_32x32x16_bf16 v[32:47], v[112:115], v[104:107], v[32:47]
	v_max3_f32 v101, v101, v70, v71
	s_nop 0
	v_max_f32_e32 v100, v100, v100
	v_max_f32_e32 v106, v88, v88
	v_max_f32_e32 v100, v100, v106
	v_max3_f32 v101, v101, v90, v91
	v_max3_f32 v100, v100, v89, v72
	v_max3_f32 v101, v101, v74, v75
	v_max3_f32 v100, v100, v73, v92
	v_max3_f32 v101, v101, v94, v95
	v_max3_f32 v100, v100, v93, v76
	v_max3_f32 v101, v101, v78, v79
	v_max3_f32 v100, v100, v77, v101
	v_mov_b32_e32 v101, v100
	s_nop 1
	v_permlane32_swap_b32_e32 v100, v101
	v_max_f32_e32 v101, v101, v101
	v_max_f32_e32 v100, v100, v100
	v_max_f32_e32 v100, v100, v101
	v_sub_f32_e32 v101, v100, v251
	s_mov_b32 s10, 0x42b504f3
	v_cmp_ge_f32_e32 vcc, s10, v101
	v_max_f32_e32 v101, v251, v251
	s_waitcnt lgkmcnt(2)
	v_mfma_f32_32x32x16_bf16 v[48:63], v[120:123], v[108:111], v[48:63]
	v_max_f32_e32 v100, v101, v100
	ds_read_b64_tr_b16 v[102:103], v226 offset:24576
	ds_read_b64_tr_b16 v[104:105], v226 offset:26624
	ds_read_b64_tr_b16 v[196:197], v226 offset:25088
	ds_read_b64_tr_b16 v[198:199], v226 offset:27136
	v_sub_f32_e32 v101, v251, v100
	v_mul_f32_e32 v101, 0x3e0293ee, v101
	v_exp_f32_e32 v101, v101
	s_cmp_eq_u64 vcc, exec
	s_cselect_b64 vcc, -1, 0
	s_waitcnt lgkmcnt(4)
	v_mfma_f32_32x32x16_bf16 v[32:47], v[120:123], v[124:127], v[32:47]
	v_cndmask_b32_e32 v192, v100, v251, vcc
	v_cndmask_b32_e64 v193, v101, 1.0, vcc
	v_mul_f32_e32 v100, 0xbe0293ee, v192
	s_waitcnt lgkmcnt(2)
	v_mfma_f32_32x32x16_bf16 v[48:63], v[116:119], v[102:105], v[48:63]
	ds_read_b64_tr_b16 v[102:103], v226 offset:28672
	ds_read_b64_tr_b16 v[104:105], v226 offset:30720
	ds_read_b64_tr_b16 v[108:109], v226 offset:31232
	ds_read_b64_tr_b16 v[106:107], v226 offset:29184
	v_fmamk_f32 v80, v80, 0x3e0293ee, v100
	v_fmamk_f32 v81, v81, 0x3e0293ee, v100
	v_fmamk_f32 v82, v82, 0x3e0293ee, v100
	v_exp_f32_e32 v80, v80
	v_exp_f32_e32 v81, v81
	v_exp_f32_e32 v82, v82
	s_waitcnt lgkmcnt(4)
	v_mfma_f32_32x32x16_bf16 v[32:47], v[116:119], v[196:199], v[32:47]
	v_fma_f32 v64, v64, s28, v100
	v_fma_f32 v65, v65, s28, v100
	v_fmamk_f32 v66, v66, 0x3e0293ee, v100
	s_waitcnt lgkmcnt(2)
	v_mfma_f32_32x32x16_bf16 v[48:63], v[96:99], v[102:105], v[48:63]
	ds_read_b64_tr_b16 v[124:125], v226 offset:17408
	ds_read_b64_tr_b16 v[126:127], v226 offset:19456
	ds_read_b64_tr_b16 v[196:197], v226 offset:17920
	ds_read_b64_tr_b16 v[198:199], v226 offset:19968
	v_fmamk_f32 v83, v83, 0x3e0293ee, v100
	v_fmamk_f32 v84, v84, 0x3e0293ee, v100
	v_fmamk_f32 v102, v67, 0x3e0293ee, v100
	v_fmamk_f32 v103, v68, 0x3e0293ee, v100
	v_fmamk_f32 v67, v85, 0x3e0293ee, v100
	s_waitcnt lgkmcnt(4)
	v_mfma_f32_32x32x16_bf16 v[32:47], v[96:99], v[106:109], v[32:47]
	v_exp_f32_e32 v83, v83
	v_exp_f32_e32 v84, v84
	v_exp_f32_e32 v85, v67
	v_fmamk_f32 v69, v69, 0x3e0293ee, v100
	v_mov_b32_e32 v67, v102
	v_mov_b32_e32 v68, v103
	s_waitcnt lgkmcnt(2)
	v_mfma_f32_32x32x16_bf16 v[16:31], v[112:115], v[124:127], v[16:31]
	ds_read_b64_tr_b16 v[102:103], v226 offset:21504
	ds_read_b64_tr_b16 v[104:105], v226 offset:23552
	ds_read_b64_tr_b16 v[108:109], v226 offset:24064
	ds_read_b64_tr_b16 v[106:107], v226 offset:22016
	v_fmamk_f32 v86, v86, 0x3e0293ee, v100
	v_fmamk_f32 v87, v87, 0x3e0293ee, v100
	v_fmamk_f32 v88, v88, 0x3e0293ee, v100
	v_exp_f32_e32 v86, v86
	v_exp_f32_e32 v87, v87
	v_exp_f32_e32 v88, v88
	s_waitcnt lgkmcnt(4)
	v_mfma_f32_32x32x16_bf16 v[0:15], v[112:115], v[196:199], v[0:15]
	v_fma_f32 v70, v70, s28, v100
	v_fma_f32 v71, v71, s28, v100
	v_fmamk_f32 v72, v72, 0x3e0293ee, v100
	s_waitcnt lgkmcnt(2)
	v_mfma_f32_32x32x16_bf16 v[16:31], v[120:123], v[102:105], v[16:31]
	ds_read_b64_tr_b16 v[110:111], v226 offset:25600
	ds_read_b64_tr_b16 v[112:113], v226 offset:27648
	ds_read_b64_tr_b16 v[124:125], v226 offset:26112
	ds_read_b64_tr_b16 v[126:127], v226 offset:28160
	v_fmamk_f32 v89, v89, 0x3e0293ee, v100
	v_fmamk_f32 v90, v90, 0x3e0293ee, v100
	v_fmamk_f32 v102, v73, 0x3e0293ee, v100
	v_fmamk_f32 v103, v74, 0x3e0293ee, v100
	v_fmamk_f32 v73, v91, 0x3e0293ee, v100
	s_waitcnt lgkmcnt(4)
	v_mfma_f32_32x32x16_bf16 v[0:15], v[120:123], v[106:109], v[0:15]
	v_exp_f32_e32 v89, v89
	v_exp_f32_e32 v90, v90
	v_exp_f32_e32 v91, v73
	v_fmamk_f32 v75, v75, 0x3e0293ee, v100
	v_mov_b32_e32 v73, v102
	v_mov_b32_e32 v74, v103
	s_waitcnt lgkmcnt(2)
	v_mfma_f32_32x32x16_bf16 v[16:31], v[116:119], v[110:113], v[16:31]
	ds_read_b64_tr_b16 v[102:103], v226 offset:29696
	ds_read_b64_tr_b16 v[104:105], v226 offset:31744
	ds_read_b64_tr_b16 v[108:109], v226 offset:32256
	ds_read_b64_tr_b16 v[106:107], v226 offset:30208
	v_fmamk_f32 v92, v92, 0x3e0293ee, v100
	v_fmamk_f32 v93, v93, 0x3e0293ee, v100
	v_exp_f32_e32 v92, v92
	v_exp_f32_e32 v93, v93
	v_fmamk_f32 v76, v76, 0x3e0293ee, v100
	v_fmamk_f32 v77, v77, 0x3e0293ee, v100
	s_waitcnt lgkmcnt(4)
	v_mfma_f32_32x32x16_bf16 v[0:15], v[116:119], v[124:127], v[0:15]
	s_waitcnt lgkmcnt(2)
	v_mfma_f32_32x32x16_bf16 v[16:31], v[96:99], v[102:105], v[16:31]
	v_mov_b32_e32 v101, v100
	v_fmamk_f32 v94, v94, 0x3e0293ee, v100
	v_fmac_f32_e32 v101, 0x3e0293ee, v95
	v_exp_f32_e32 v94, v94
	v_exp_f32_e32 v95, v101
	v_fmamk_f32 v78, v78, 0x3e0293ee, v100
	v_fmamk_f32 v79, v79, 0x3e0293ee, v100
	s_waitcnt lgkmcnt(0)
	v_mfma_f32_32x32x16_bf16 v[0:15], v[96:99], v[106:109], v[0:15]
	s_waitcnt vmcnt(4)
	v_cmp_gt_f32_e32 vcc, 1.0, v193
	s_waitcnt vmcnt(1)
	ds_write_b128 v229, v[184:187] offset:49152
	s_waitcnt vmcnt(0)
	ds_write_b128 v231, v[188:191] offset:49152
	s_cbranch_vccz .LBB0_494
	s_and_saveexec_b64 s[16:17], s[36:37]
	ds_write_b32 v240, v193 offset:128
	s_or_b64 exec, exec, s[16:17]
	s_waitcnt lgkmcnt(0)
	v_add_u32_e32 v108, s31, v224
	ds_read_b128 v[96:99], v108 offset:224
	ds_read_b128 v[100:103], v108 offset:192
	ds_read_b128 v[104:107], v108 offset:128
	ds_read_b128 v[108:111], v108 offset:160
	s_waitcnt lgkmcnt(3)
	v_pk_mul_f32 v[62:63], v[62:63], v[98:99]
	v_pk_mul_f32 v[60:61], v[60:61], v[96:97]
	s_waitcnt lgkmcnt(2)
	v_pk_mul_f32 v[58:59], v[58:59], v[102:103]
	v_pk_mul_f32 v[56:57], v[56:57], v[100:101]
	s_waitcnt lgkmcnt(0)
	v_pk_mul_f32 v[54:55], v[54:55], v[110:111]
	v_pk_mul_f32 v[52:53], v[52:53], v[108:109]
	v_pk_mul_f32 v[50:51], v[50:51], v[106:107]
	v_pk_mul_f32 v[48:49], v[48:49], v[104:105]
	v_pk_mul_f32 v[46:47], v[46:47], v[98:99]
	v_pk_mul_f32 v[44:45], v[44:45], v[96:97]
	v_pk_mul_f32 v[42:43], v[42:43], v[102:103]
	v_pk_mul_f32 v[40:41], v[40:41], v[100:101]
	v_pk_mul_f32 v[38:39], v[38:39], v[110:111]
	v_pk_mul_f32 v[36:37], v[36:37], v[108:109]
	v_pk_mul_f32 v[34:35], v[34:35], v[106:107]
	v_pk_mul_f32 v[32:33], v[32:33], v[104:105]
	v_pk_mul_f32 v[30:31], v[30:31], v[98:99]
	v_pk_mul_f32 v[28:29], v[28:29], v[96:97]
	v_pk_mul_f32 v[26:27], v[26:27], v[102:103]
	v_pk_mul_f32 v[24:25], v[24:25], v[100:101]
	v_pk_mul_f32 v[22:23], v[22:23], v[110:111]
	v_pk_mul_f32 v[20:21], v[20:21], v[108:109]
	v_pk_mul_f32 v[18:19], v[18:19], v[106:107]
	v_pk_mul_f32 v[16:17], v[16:17], v[104:105]
	v_pk_mul_f32 v[14:15], v[14:15], v[98:99]
	v_pk_mul_f32 v[12:13], v[12:13], v[96:97]
	v_pk_mul_f32 v[10:11], v[10:11], v[102:103]
	v_pk_mul_f32 v[8:9], v[8:9], v[100:101]
	v_pk_mul_f32 v[6:7], v[6:7], v[110:111]
	v_pk_mul_f32 v[4:5], v[4:5], v[108:109]
	v_pk_mul_f32 v[2:3], v[2:3], v[106:107]
	v_pk_mul_f32 v[0:1], v[0:1], v[104:105]

.LBB0_510:
	s_waitcnt lgkmcnt(0)
	s_nop 0
	v_mfma_f32_32x32x16_bf16 v[112:127], v[164:167], v[156:159], v[112:127]
	ds_read_b128 v[168:171], v237 offset:49152
	ds_read_b128 v[172:175], v237 offset:57344
	v_add_f32_e32 v176, v80, v81
	v_add_f32_e32 v164, v82, v176
	v_exp_f32_e32 v64, v64
	v_exp_f32_e32 v65, v65
	v_exp_f32_e32 v66, v66
	v_add_f32_e32 v164, v83, v164
	v_mfma_f32_32x32x16_bf16 v[96:111], v[160:163], v[156:159], v[96:111]
	v_cvt_pk_bf16_f32 v80, v80, v81
	v_cvt_pk_bf16_f32 v81, v82, v83
	s_nop 0
	s_waitcnt lgkmcnt(1)
	v_mfma_f32_32x32x16_bf16 v[112:127], v[168:171], v[152:155], v[112:127]
	ds_read_b128 v[156:159], v236 offset:49152
	ds_read_b128 v[160:163], v236 offset:57344
	v_add_f32_e32 v82, v84, v164
	v_add_f32_e32 v82, v85, v82
	v_add_f32_e32 v82, v86, v82
	v_add_f32_e32 v164, v87, v82
	v_cvt_pk_bf16_f32 v82, v84, v85
	v_cvt_pk_bf16_f32 v83, v86, v87
	s_waitcnt lgkmcnt(2)
	v_mfma_f32_32x32x16_bf16 v[96:111], v[172:175], v[152:155], v[96:111]
	v_exp_f32_e32 v67, v67
	v_exp_f32_e32 v68, v68
	v_exp_f32_e32 v69, v69
	v_permlane32_swap_b32_e32 v80, v82
	v_permlane32_swap_b32_e32 v81, v83
	s_waitcnt lgkmcnt(1)
	v_mfma_f32_32x32x16_bf16 v[112:127], v[156:159], v[148:151], v[112:127]
	ds_read_b128 v[84:87], v235 offset:49152
	ds_read_b128 v[152:155], v235 offset:57344
	v_add_f32_e32 v164, v88, v164
	v_add_f32_e32 v156, v89, v164
	v_add_f32_e32 v156, v90, v156
	v_exp_f32_e32 v70, v70
	v_exp_f32_e32 v71, v71
	v_exp_f32_e32 v72, v72
	s_waitcnt lgkmcnt(2)
	v_mfma_f32_32x32x16_bf16 v[96:111], v[160:163], v[148:151], v[96:111]
	v_add_f32_e32 v164, v91, v156
	v_cvt_pk_bf16_f32 v88, v88, v89
	v_cvt_pk_bf16_f32 v89, v90, v91
	s_nop 0
	s_waitcnt lgkmcnt(1)
	v_mfma_f32_32x32x16_bf16 v[112:127], v[84:87], v[144:147], v[112:127]
	ds_read_b128 v[148:151], v234 offset:49152
	ds_read_b128 v[156:159], v234 offset:57344
	v_add_f32_e32 v90, v92, v164
	v_add_f32_e32 v84, v93, v90
	v_add_f32_e32 v84, v94, v84
	v_cvt_pk_bf16_f32 v90, v92, v93
	v_cvt_pk_bf16_f32 v91, v94, v95
	v_exp_f32_e32 v73, v73
	s_waitcnt lgkmcnt(2)
	v_mfma_f32_32x32x16_bf16 v[96:111], v[152:155], v[144:147], v[96:111]
	v_exp_f32_e32 v74, v74
	v_exp_f32_e32 v75, v75
	v_add_f32_e32 v84, v95, v84
	v_permlane32_swap_b32_e32 v88, v90
	v_permlane32_swap_b32_e32 v89, v91
	s_waitcnt lgkmcnt(1)
	v_mfma_f32_32x32x16_bf16 v[112:127], v[148:151], v[140:143], v[112:127]
	ds_read_b128 v[92:95], v233 offset:49152
	ds_read_b128 v[144:147], v233 offset:57344
	v_add_f32_e32 v84, v84, v64
	v_add_f32_e32 v84, v65, v84
	v_add_f32_e32 v84, v66, v84
	v_exp_f32_e32 v76, v76
	v_exp_f32_e32 v77, v77
	v_add_f32_e32 v86, v67, v84
	s_waitcnt lgkmcnt(2)
	v_mfma_f32_32x32x16_bf16 v[96:111], v[156:159], v[140:143], v[96:111]
	v_cvt_pk_bf16_f32 v84, v64, v65
	v_cvt_pk_bf16_f32 v85, v66, v67
	s_nop 0
	s_waitcnt lgkmcnt(1)
	v_mfma_f32_32x32x16_bf16 v[112:127], v[92:95], v[136:139], v[112:127]
	ds_read_b128 v[140:143], v232 offset:49152
	ds_read_b128 v[148:151], v232 offset:57344
	v_add_f32_e32 v86, v86, v68
	v_add_f32_e32 v86, v69, v86
	v_add_f32_e32 v86, v70, v86
	v_add_f32_e32 v152, v71, v86
	v_cvt_pk_bf16_f32 v86, v68, v69
	v_cvt_pk_bf16_f32 v87, v70, v71
	s_waitcnt lgkmcnt(2)
	v_mfma_f32_32x32x16_bf16 v[96:111], v[144:147], v[136:139], v[96:111]
	v_exp_f32_e32 v78, v78
	v_exp_f32_e32 v79, v79
	v_permlane32_swap_b32_e32 v84, v86
	v_permlane32_swap_b32_e32 v85, v87
	s_waitcnt lgkmcnt(1)
	v_mfma_f32_32x32x16_bf16 v[112:127], v[140:143], v[132:135], v[112:127]
	ds_read_b128 v[66:69], v230 offset:49152
	ds_read_b128 v[92:95], v230 offset:57344
	v_add_f32_e32 v64, v152, v72
	v_add_f32_e32 v64, v73, v64
	v_add_f32_e32 v64, v74, v64
	v_add_f32_e32 v70, v75, v64
	v_cvt_pk_bf16_f32 v64, v72, v73
	v_cvt_pk_bf16_f32 v65, v74, v75
	s_waitcnt lgkmcnt(2)
	v_mfma_f32_32x32x16_bf16 v[96:111], v[148:151], v[132:135], v[96:111]
	s_waitcnt lgkmcnt(1)
	v_mfma_f32_32x32x16_bf16 v[112:127], v[66:69], v[128:131], v[112:127]
	v_add_f32_e32 v66, v76, v70
	v_add_f32_e32 v66, v77, v66
	v_add_f32_e32 v66, v78, v66
	v_add_f32_e32 v68, v79, v66
	v_mov_b32_e32 v69, v68
	s_nop 1
	v_permlane32_swap_b32_e32 v68, v69
	s_waitcnt lgkmcnt(0)
	v_mfma_f32_32x32x16_bf16 v[96:111], v[92:95], v[128:131], v[96:111]
	ds_read_b64_tr_b16 v[72:73], v226
	ds_read_b64_tr_b16 v[74:75], v226 offset:2048
	ds_read_b64_tr_b16 v[92:93], v226 offset:512
	ds_read_b64_tr_b16 v[94:95], v226 offset:2560
	v_cvt_pk_bf16_f32 v66, v76, v77
	v_cvt_pk_bf16_f32 v67, v78, v79
	v_add_f32_e32 v70, v68, v69
	v_permlane32_swap_b32_e32 v64, v66
	v_permlane32_swap_b32_e32 v65, v67
	v_fmac_f32_e32 v70, v194, v193
	s_waitcnt lgkmcnt(2)
	v_mfma_f32_32x32x16_bf16 v[48:63], v[80:83], v[72:75], v[48:63]
	ds_read_b64_tr_b16 v[76:77], v226 offset:4096
	ds_read_b64_tr_b16 v[78:79], v226 offset:6144
	ds_read_b64_tr_b16 v[128:129], v226 offset:4608
	ds_read_b64_tr_b16 v[130:131], v226 offset:6656
	v_max3_f32 v68, v112, v113, v96
	v_max3_f32 v69, v114, v115, v97
	v_max3_f32 v68, v68, v98, v99
	v_max3_f32 v68, v68, v116, v117
	v_max3_f32 v69, v69, v118, v119
	v_max3_f32 v68, v68, v100, v101
	s_waitcnt lgkmcnt(4)
	v_mfma_f32_32x32x16_bf16 v[32:47], v[80:83], v[92:95], v[32:47]
	v_max3_f32 v69, v69, v102, v103
	s_nop 0
	v_max_f32_e32 v68, v68, v68
	v_max_f32_e32 v71, v120, v120
	v_max_f32_e32 v68, v68, v71
	v_max3_f32 v69, v69, v122, v123
	v_max3_f32 v68, v68, v121, v104
	v_max3_f32 v69, v69, v106, v107
	v_max3_f32 v68, v68, v105, v124
	v_max3_f32 v69, v69, v126, v127
	v_max3_f32 v68, v68, v125, v108
	v_max3_f32 v69, v69, v110, v111
	v_max3_f32 v68, v68, v109, v69
	v_mov_b32_e32 v69, v68
	s_nop 1
	v_permlane32_swap_b32_e32 v68, v69
	v_max_f32_e32 v69, v69, v69
	v_max_f32_e32 v68, v68, v68
	v_max_f32_e32 v68, v68, v69
	v_sub_f32_e32 v69, v68, v192
	s_mov_b32 s1, 0x42b504f3
	v_cmp_ge_f32_e32 vcc, s1, v69
	v_max_f32_e32 v69, v192, v192
	s_waitcnt lgkmcnt(2)
	v_mfma_f32_32x32x16_bf16 v[48:63], v[88:91], v[76:79], v[48:63]
	v_max_f32_e32 v68, v69, v68
	ds_read_b64_tr_b16 v[72:73], v226 offset:8192
	ds_read_b64_tr_b16 v[74:75], v226 offset:10240
	ds_read_b64_tr_b16 v[92:93], v226 offset:8704
	ds_read_b64_tr_b16 v[94:95], v226 offset:10752
	v_sub_f32_e32 v69, v192, v68
	v_mul_f32_e32 v69, 0x3e0293ee, v69
	v_exp_f32_e32 v71, v69
	s_cmp_eq_u64 vcc, exec
	s_cselect_b64 vcc, -1, 0
	s_waitcnt lgkmcnt(4)
	v_mfma_f32_32x32x16_bf16 v[32:47], v[88:91], v[128:131], v[32:47]
	v_cndmask_b32_e32 v69, v68, v192, vcc
	v_cndmask_b32_e64 v71, v71, 1.0, vcc
	v_mul_f32_e32 v68, 0xbe0293ee, v69
	s_nop 0
	v_fmamk_f32 v76, v112, 0x3e0293ee, v68
	v_exp_f32_e32 v112, v76
	v_fmamk_f32 v76, v113, 0x3e0293ee, v68
	v_exp_f32_e32 v113, v76
	v_fmamk_f32 v76, v114, 0x3e0293ee, v68
	s_waitcnt lgkmcnt(2)
	v_mfma_f32_32x32x16_bf16 v[48:63], v[84:87], v[72:75], v[48:63]
	v_exp_f32_e32 v114, v76
	ds_read_b64_tr_b16 v[72:73], v226 offset:12288
	ds_read_b64_tr_b16 v[74:75], v226 offset:14336
	ds_read_b64_tr_b16 v[78:79], v226 offset:14848
	ds_read_b64_tr_b16 v[76:77], v226 offset:12800
	v_fmamk_f32 v96, v96, 0x3e0293ee, v68
	v_fmamk_f32 v97, v97, 0x3e0293ee, v68
	v_fmamk_f32 v98, v98, 0x3e0293ee, v68
	s_waitcnt lgkmcnt(4)
	v_mfma_f32_32x32x16_bf16 v[32:47], v[84:87], v[92:95], v[32:47]
	s_waitcnt lgkmcnt(2)
	v_mfma_f32_32x32x16_bf16 v[48:63], v[64:67], v[72:75], v[48:63]
	ds_read_b64_tr_b16 v[92:93], v226 offset:1024
	ds_read_b64_tr_b16 v[94:95], v226 offset:3072
	ds_read_b64_tr_b16 v[128:129], v226 offset:1536
	ds_read_b64_tr_b16 v[130:131], v226 offset:3584
	v_fmamk_f32 v72, v115, 0x3e0293ee, v68
	v_exp_f32_e32 v115, v72
	v_fmamk_f32 v72, v116, 0x3e0293ee, v68
	v_exp_f32_e32 v116, v72
	v_mov_b32_e32 v72, v99
	v_mov_b32_e32 v73, v100
	s_waitcnt lgkmcnt(4)
	v_mfma_f32_32x32x16_bf16 v[32:47], v[64:67], v[76:79], v[32:47]
	v_fma_f32 v72, v72, s28, v68
	v_fma_f32 v73, v73, s28, v68
	v_fmamk_f32 v74, v117, 0x3e0293ee, v68
	v_exp_f32_e32 v117, v74
	v_fmamk_f32 v101, v101, 0x3e0293ee, v68
	v_mov_b32_e32 v99, v72
	v_mov_b32_e32 v100, v73
	s_nop 0
	v_fmamk_f32 v72, v118, 0x3e0293ee, v68
	v_exp_f32_e32 v118, v72
	v_fmamk_f32 v72, v119, 0x3e0293ee, v68
	v_exp_f32_e32 v119, v72
	v_fmamk_f32 v72, v120, 0x3e0293ee, v68
	s_waitcnt lgkmcnt(2)
	v_mfma_f32_32x32x16_bf16 v[16:31], v[80:83], v[92:95], v[16:31]
	v_exp_f32_e32 v120, v72
	ds_read_b64_tr_b16 v[72:73], v226 offset:5120
	ds_read_b64_tr_b16 v[74:75], v226 offset:7168
	ds_read_b64_tr_b16 v[78:79], v226 offset:7680
	ds_read_b64_tr_b16 v[76:77], v226 offset:5632
	v_fmamk_f32 v102, v102, 0x3e0293ee, v68
	v_fmamk_f32 v103, v103, 0x3e0293ee, v68
	v_fmamk_f32 v104, v104, 0x3e0293ee, v68
	s_waitcnt lgkmcnt(4)
	v_mfma_f32_32x32x16_bf16 v[0:15], v[80:83], v[128:131], v[0:15]
	s_waitcnt lgkmcnt(2)
	v_mfma_f32_32x32x16_bf16 v[16:31], v[88:91], v[72:75], v[16:31]
	ds_read_b64_tr_b16 v[80:81], v226 offset:9216
	ds_read_b64_tr_b16 v[82:83], v226 offset:11264
	ds_read_b64_tr_b16 v[92:93], v226 offset:9728
	ds_read_b64_tr_b16 v[94:95], v226 offset:11776
	v_fmamk_f32 v72, v121, 0x3e0293ee, v68
	v_exp_f32_e32 v121, v72
	v_fmamk_f32 v72, v122, 0x3e0293ee, v68
	v_exp_f32_e32 v122, v72
	v_mov_b32_e32 v72, v105
	v_mov_b32_e32 v73, v106
	s_waitcnt lgkmcnt(4)
	v_mfma_f32_32x32x16_bf16 v[0:15], v[88:91], v[76:79], v[0:15]
	v_fma_f32 v72, v72, s28, v68
	v_fma_f32 v73, v73, s28, v68
	v_fmamk_f32 v74, v123, 0x3e0293ee, v68
	v_exp_f32_e32 v123, v74
	v_fmamk_f32 v107, v107, 0x3e0293ee, v68
	v_mov_b32_e32 v105, v72
	v_mov_b32_e32 v106, v73
	s_nop 0
	v_fmamk_f32 v72, v124, 0x3e0293ee, v68
	v_exp_f32_e32 v124, v72
	v_fmamk_f32 v72, v125, 0x3e0293ee, v68
	s_waitcnt lgkmcnt(2)
	v_mfma_f32_32x32x16_bf16 v[16:31], v[84:87], v[80:83], v[16:31]
	v_exp_f32_e32 v125, v72
	ds_read_b64_tr_b16 v[72:73], v226 offset:13312
	ds_read_b64_tr_b16 v[74:75], v226 offset:15360
	ds_read_b64_tr_b16 v[78:79], v226 offset:15872
	ds_read_b64_tr_b16 v[76:77], v226 offset:13824
	v_fmamk_f32 v108, v108, 0x3e0293ee, v68
	v_fmamk_f32 v109, v109, 0x3e0293ee, v68
	s_nop 0
	s_waitcnt lgkmcnt(4)
	v_mfma_f32_32x32x16_bf16 v[0:15], v[84:87], v[92:95], v[0:15]
	s_waitcnt lgkmcnt(2)
	v_mfma_f32_32x32x16_bf16 v[16:31], v[64:67], v[72:75], v[16:31]
	v_fmamk_f32 v72, v126, 0x3e0293ee, v68
	v_exp_f32_e32 v126, v72
	v_mov_b32_e32 v72, v68
	v_fmac_f32_e32 v72, 0x3e0293ee, v127
	v_exp_f32_e32 v127, v72
	v_fmamk_f32 v110, v110, 0x3e0293ee, v68
	v_fmamk_f32 v111, v111, 0x3e0293ee, v68
	s_waitcnt lgkmcnt(0)
	v_mfma_f32_32x32x16_bf16 v[0:15], v[64:67], v[76:79], v[0:15]
	v_cmp_gt_f32_e32 vcc, 1.0, v71
	s_cbranch_vccz .LBB0_514
	v_cmp_gt_u32_e32 vcc, 32, v200
	s_and_saveexec_b64 s[2:3], vcc
	v_readlane_b32 s22, v254, 46
	v_readlane_b32 s23, v254, 47
	v_lshl_add_u32 v64, v221, 2, s31
	ds_write_b32 v64, v71 offset:128
	s_or_b64 exec, exec, s[2:3]
	s_waitcnt lgkmcnt(0)
	v_add_u32_e32 v68, s31, v224
	ds_read_b128 v[64:67], v68 offset:224
	ds_read_b128 v[72:75], v68 offset:192
	ds_read_b128 v[76:79], v68 offset:160
	ds_read_b128 v[80:83], v68 offset:128
	s_waitcnt lgkmcnt(3)
	v_pk_mul_f32 v[60:61], v[60:61], v[64:65]
	s_waitcnt lgkmcnt(2)
	v_pk_mul_f32 v[56:57], v[56:57], v[72:73]
	s_waitcnt lgkmcnt(1)
	v_pk_mul_f32 v[52:53], v[52:53], v[76:77]
	v_pk_mul_f32 v[62:63], v[62:63], v[66:67]
	v_pk_mul_f32 v[58:59], v[58:59], v[74:75]
	v_pk_mul_f32 v[54:55], v[54:55], v[78:79]
	s_waitcnt lgkmcnt(0)
	v_pk_mul_f32 v[50:51], v[50:51], v[82:83]
	v_pk_mul_f32 v[48:49], v[48:49], v[80:81]
	v_pk_mul_f32 v[44:45], v[44:45], v[64:65]
	v_pk_mul_f32 v[40:41], v[40:41], v[72:73]
	v_pk_mul_f32 v[36:37], v[36:37], v[76:77]
	v_pk_mul_f32 v[46:47], v[46:47], v[66:67]
	v_pk_mul_f32 v[42:43], v[42:43], v[74:75]
	v_pk_mul_f32 v[38:39], v[38:39], v[78:79]
	v_pk_mul_f32 v[34:35], v[34:35], v[82:83]
	v_pk_mul_f32 v[32:33], v[32:33], v[80:81]
	v_pk_mul_f32 v[28:29], v[28:29], v[64:65]
	v_pk_mul_f32 v[24:25], v[24:25], v[72:73]
	v_pk_mul_f32 v[20:21], v[20:21], v[76:77]
	v_pk_mul_f32 v[30:31], v[30:31], v[66:67]
	v_pk_mul_f32 v[26:27], v[26:27], v[74:75]
	v_pk_mul_f32 v[22:23], v[22:23], v[78:79]
	v_pk_mul_f32 v[18:19], v[18:19], v[82:83]
	v_pk_mul_f32 v[16:17], v[16:17], v[80:81]
	v_pk_mul_f32 v[12:13], v[12:13], v[64:65]
	v_pk_mul_f32 v[8:9], v[8:9], v[72:73]
	v_pk_mul_f32 v[4:5], v[4:5], v[76:77]
	v_pk_mul_f32 v[14:15], v[14:15], v[66:67]
	v_pk_mul_f32 v[10:11], v[10:11], v[74:75]
	v_pk_mul_f32 v[6:7], v[6:7], v[78:79]
	v_pk_mul_f32 v[2:3], v[2:3], v[82:83]
	v_pk_mul_f32 v[0:1], v[0:1], v[80:81]
	s_branch .LBB0_515
